# weight-conversion strip loops (gate/up, down, NSA w1): two-tile-deep register prefetch ring (loop unrolled x2), counted vmcnt instead of vmcnt(0), pos-bias prefetch
# speedup vs baseline: 1.0088x; 1.0011x over previous
; #define LAS __attribute__((address_space(3)))
; DI float h2f(bf16_t v) { return (float)__builtin_bit_cast(_Float16, v); }
; DI float bf2f(bf16_t v) { return __uint_as_float(((unsigned)v) << 16); }
; DI void lds_barrier() { asm volatile("s_waitcnt lgkmcnt(0)\n\ts_barrier" ::: "memory"); }
;     ...
;   for (int rr = 0; rr < 2; ++rr) w[rr] = colok ? *(const f32x4*)(src + (size_t)(kbeg + kr + rr * 32) * ldn + n0 + nc) : (f32x4){0.f, 0.f, 0.f, 0.f};
;   for (int k0 = kbeg; k0 < kend; k0 += 64) {
;     lds_barrier();
; #pragma unroll
;     for (int rr = 0; rr < 2; ++rr) { const int k = k0 + kr + rr * 32; const float gk = g ? g[k] : 1.0f, bk = b ? b[k] : 0.0f;
; #pragma unroll
;       for (int j = 0; j < 4; ++j) { const bf16_t v = perm ? f2h(w[rr][j] * gk) : f2bf(w[rr][j] * gk); tile[(nc + j) * 72 + kr + rr * 32] = v; s1[j] += perm ? h2f(v) : bf2f(v); s2[j] += bk * w[rr][j]; } }
;     if (k0 + 64 < kend) {
; #pragma unroll
;       for (int rr = 0; rr < 2; ++rr) w[rr] = colok ? *(const f32x4*)(src + (size_t)(k0 + 64 + kr + rr * 32) * ldn + n0 + nc) : (f32x4){0.f, 0.f, 0.f, 0.f};
;     }
;     lds_barrier();
;     { const int n = tid >> 3, kc = (tid & 7) * 8; const int cc = n & 31, slot = (n & 32) + (perm ? 16 * ((cc >> 2) & 1) + 4 * (cc >> 3) + (cc & 3) : cc);
;       *(u32x4*)(dst + (size_t)(dstrow0 + slot) * K + k0 + kc) = *(const LAS u32x4*)(tile + n * 72 + kc); }
;   }
.LBB0_44:
	s_andn2_b64 vcc, exec, s[0:1]
	s_cbranch_vccnz .LBB0_57
	s_add_i32 s0, s27, 0xfffffee0
	s_ashr_i32 s0, s0, 1
	s_bfe_u32 s34, s86, 0x10006
	s_ashr_i32 s1, s0, 31
	s_lshl_b32 s35, s34, 8
	s_lshl_b64 s[6:7], s[0:1], 11
	v_readlane_b32 s4, v255, 32
	v_readlane_b32 s5, v255, 33
	s_add_u32 s6, s6, s4
	s_addc_u32 s7, s7, s5
	v_readlane_b32 s60, v252, 32
	s_lshl_b64 s[6:7], s[6:7], 9
	v_readlane_b32 s70, v252, 42
	v_readlane_b32 s69, v252, 41
	v_readlane_b32 s71, v252, 43
	s_add_u32 s30, s70, s6
	s_mov_b32 s69, s48
	s_addc_u32 s31, s71, s7
	s_lshl_b32 s6, s87, 6
	s_and_b32 s29, s6, 64
	s_waitcnt vmcnt(1)
	v_mbcnt_lo_u32_b32 v0, -1, 0
	v_mbcnt_hi_u32_b32 v0, -1, v0
	s_lshl_b64 s[6:7], s[0:1], 19
	v_add_u32_e32 v33, s69, v0
	s_lshl_b32 s36, s29, 2
	v_lshlrev_b32_e32 v0, 2, v33
	v_ashrrev_i32_e32 v24, 4, v33
	v_and_b32_e32 v10, 60, v0
	s_add_u32 s30, s30, s36
	s_addc_u32 s31, s31, 0
	v_lshlrev_b32_e32 v26, 2, v10
	v_mov_b32_e32 v27, v32
	v_ashrrev_i32_e32 v25, 31, v24
	v_lshl_add_u64 v[0:1], s[30:31], 0, v[26:27]
	v_lshlrev_b64 v[8:9], 9, v[24:25]
	v_lshl_add_u64 v[0:1], v[0:1], 0, v[8:9]
	s_movk_i32 s4, 0x4000
	v_add_co_u32_e32 v2, vcc, s4, v0
	v_ashrrev_i32_e32 v11, 3, v33
	s_nop 0
	v_addc_co_u32_e32 v3, vcc, 0, v1, vcc
	global_load_dwordx4 v[4:7], v[0:1], off
	s_nop 0
	global_load_dwordx4 v[0:3], v[2:3], off
	v_lshlrev_b32_e32 v14, 4, v33
	v_mul_lo_u32 v13, v11, s90
	v_and_b32_e32 v14, 0x70, v14
	v_lshlrev_b32_e32 v11, 12, v11
	v_add3_u32 v27, 0, v13, v14
	v_mul_u32_u24_e32 v13, 0x90, v10
	v_and_b32_e32 v10, 7, v33
	v_and_b32_e32 v11, 0x3f000, v11
	v_lshlrev_b32_e32 v10, 4, v10
	v_lshl_or_b32 v11, s34, 18, v11
	v_or3_b32 v10, s6, v10, v11
	v_mov_b32_e32 v11, s7
	v_lshl_add_u64 v[28:29], s[20:21], 0, v[10:11]
	s_lshl_b64 s[6:7], s[0:1], 20
	v_and_b32_e32 v10, 15, v33
	v_lshl_add_u64 v[8:9], s[6:7], 0, v[8:9]
	v_lshlrev_b32_e32 v10, 4, v10
	v_readlane_b32 s4, v255, 34
	s_lshl_b64 s[6:7], s[0:1], 13
	v_readlane_b32 s1, v255, 45
	v_or3_b32 v8, v8, s35, v10
	v_readlane_b32 s5, v255, 35
	s_add_u32 s6, s1, s6
	v_readlane_b32 s1, v255, 46
	v_lshl_add_u32 v12, v24, 1, 0
	v_lshl_add_u64 v[30:31], s[4:5], 0, v[8:9]
	s_addc_u32 s7, s1, s7
	v_mov_b32_e32 v8, 0
	v_readlane_b32 s4, v252, 52
	s_mov_b32 s30, 0
	v_lshl_add_u64 v[34:35], v[24:25], 2, s[6:7]
	v_add_u32_e32 v25, v12, v13
	v_mov_b32_e32 v9, v8
	v_mov_b32_e32 v10, v8
	v_mov_b32_e32 v11, v8
	v_mov_b32_e32 v12, v8
	v_mov_b32_e32 v13, v8
	v_mov_b32_e32 v14, v8
	v_mov_b32_e32 v15, v8
	v_readlane_b32 s5, v252, 53
	v_readlane_b32 s61, v252, 33
	v_readlane_b32 s62, v252, 34
	v_readlane_b32 s63, v252, 35
	v_readlane_b32 s64, v252, 36
	v_readlane_b32 s65, v252, 37
	v_readlane_b32 s66, v252, 38
	v_readlane_b32 s67, v252, 39
	v_readlane_b32 s68, v252, 40
	v_readlane_b32 s72, v252, 44
	v_readlane_b32 s73, v252, 45
	v_readlane_b32 s74, v252, 46
	v_readlane_b32 s75, v252, 47
	s_mov_b64 s[98:99], 0x8000
	s_mov_b64 s[100:101], 0x4000
	s_and_b64 vcc, exec, s[4:5]
	s_cbranch_vccz .Lc47_nb0
	global_load_dword v216, v[34:35], off offset:-128
	global_load_dword v217, v[34:35], off
.Lc47_nb0:
	v_add_co_u32_e32 v244, vcc, 0xffffc000, v30
	s_nop 1
	v_addc_co_u32_e32 v245, vcc, -1, v31, vcc
	global_load_dwordx4 v[244:247], v[244:245], off
	s_nop 0
	global_load_dwordx4 v[248:251], v[30:31], off
	s_waitcnt vmcnt(2)
	s_branch .LBB0_47
.LBB0_47:
	s_waitcnt lgkmcnt(0)
	s_barrier
	v_mov_b32_e32 v36, 0
	v_mov_b32_e32 v38, 0
	s_and_b64 vcc, exec, s[4:5]
	s_cbranch_vccz .Lc47a_nob
	v_mov_b32_e32 v36, v216
	v_mov_b32_e32 v38, v217
.Lc47a_nob:
	v_cvt_pk_bf16_f32 v39, v4, v5
	v_cvt_pk_bf16_f32 v37, v6, v7
	ds_write_b16 v25, v39
	ds_write_b16_d16_hi v25, v39 offset:144
	ds_write_b16 v25, v37 offset:288
	ds_write_b16_d16_hi v25, v37 offset:432
	s_cmpk_gt_u32 s30, 0x7bf
	v_cvt_pk_bf16_f32 v41, v0, v1
	v_cvt_pk_bf16_f32 v40, v2, v3
	s_cselect_b64 s[6:7], -1, 0
	s_cmpk_lt_u32 s30, 0x7c0
	ds_write_b16 v25, v41 offset:64
	ds_write_b16_d16_hi v25, v41 offset:208
	ds_write_b16 v25, v40 offset:352
	ds_write_b16_d16_hi v25, v40 offset:496
	s_cbranch_scc0 .Lc47a_46
	s_and_b64 vcc, exec, s[4:5]
	s_cbranch_vccz .Lc47a_nbl
	global_load_dword v216, v[34:35], off offset:128
	global_load_dword v217, v[34:35], off offset:256
.Lc47a_nbl:
	s_cmpk_lt_u32 s30, 0x780
	s_cbranch_scc0 .Lc47a_46
	v_lshl_add_u64 v[220:221], v[30:31], 0, s[100:101]
	v_lshl_add_u64 v[224:225], v[30:31], 0, s[98:99]
	global_load_dwordx4 v[220:223], v[220:221], off
	s_nop 0
	global_load_dwordx4 v[224:227], v[224:225], off
.Lc47a_46:
	v_and_b32_e32 v43, 0xffff0000, v39
	v_lshlrev_b32_e32 v42, 16, v39
	v_pk_add_f32 v[8:9], v[8:9], v[42:43]
	v_pk_fma_f32 v[4:5], v[4:5], v[36:37], v[12:13] op_sel_hi:[1,0,1]
	v_and_b32_e32 v13, 0xffff0000, v37
	v_lshlrev_b32_e32 v12, 16, v37
	v_pk_fma_f32 v[14:15], v[6:7], v[36:37], v[14:15] op_sel_hi:[1,0,1]
	v_and_b32_e32 v7, 0xffff0000, v41
	v_lshlrev_b32_e32 v6, 16, v41
	s_waitcnt lgkmcnt(0)
	s_barrier
	v_pk_add_f32 v[10:11], v[10:11], v[12:13]
	v_pk_add_f32 v[8:9], v[8:9], v[6:7]
	v_pk_fma_f32 v[12:13], v[0:1], v[38:39], v[4:5] op_sel_hi:[1,0,1]
	ds_read_b128 v[4:7], v27
	v_and_b32_e32 v1, 0xffff0000, v40
	v_lshlrev_b32_e32 v0, 16, v40
	s_mov_b64 s[34:35], 0x8000
	v_pk_add_f32 v[10:11], v[10:11], v[0:1]
	v_pk_fma_f32 v[14:15], v[2:3], v[38:39], v[14:15] op_sel_hi:[1,0,1]
	s_add_i32 s30, s30, 64
	s_waitcnt lgkmcnt(0)
	global_store_dwordx4 v[28:29], v[4:7], off
	v_lshl_add_u64 v[28:29], v[28:29], 0, s[2:3]
	v_lshl_add_u64 v[30:31], v[30:31], 0, s[34:35]
	v_lshl_add_u64 v[34:35], v[34:35], 0, s[8:9]
	s_and_b64 vcc, exec, s[6:7]
	s_cbranch_vccnz .LBB0_54
	s_cmpk_lt_u32 s30, 0x7c0
	s_cbranch_scc1 .Lc47a_w3
	s_waitcnt vmcnt(1)
	s_branch .Lc47a_cp
.Lc47a_w3:
	s_waitcnt vmcnt(3)
.Lc47a_cp:
	v_mov_b32_e32 v4, v244
	v_mov_b32_e32 v5, v245
	v_mov_b32_e32 v6, v246
	v_mov_b32_e32 v7, v247
	v_mov_b32_e32 v0, v248
	v_mov_b32_e32 v1, v249
	v_mov_b32_e32 v2, v250
	v_mov_b32_e32 v3, v251

;     ...
;     if (k0 + 64 < kend) {
; #pragma unroll
;       for (int rr = 0; rr < 2; ++rr) w[rr] = colok ? *(const f32x4*)(src + (size_t)(k0 + 64 + kr + rr * 32) * ldn + n0 + nc) : (f32x4){0.f, 0.f, 0.f, 0.f};
;     }
.Lc47b_nbl:
	s_cmpk_lt_u32 s30, 0x780
	s_cbranch_scc0 .Lc47b_46
	v_lshl_add_u64 v[244:245], v[30:31], 0, s[100:101]
	v_lshl_add_u64 v[248:249], v[30:31], 0, s[98:99]
	global_load_dwordx4 v[244:247], v[244:245], off
	s_nop 0
	global_load_dwordx4 v[248:251], v[248:249], off

;     ...
;     if (k0 + 64 < kend) {
; #pragma unroll
;       for (int rr = 0; rr < 2; ++rr) w[rr] = colok ? *(const f32x4*)(src + (size_t)(k0 + 64 + kr + rr * 32) * ldn + n0 + nc) : (f32x4){0.f, 0.f, 0.f, 0.f};
;     }
.Lc47b_cp:
	v_mov_b32_e32 v4, v220
	v_mov_b32_e32 v5, v221
	v_mov_b32_e32 v6, v222
	v_mov_b32_e32 v7, v223
	v_mov_b32_e32 v0, v224
	v_mov_b32_e32 v1, v225
	v_mov_b32_e32 v2, v226
	v_mov_b32_e32 v3, v227
	s_branch .LBB0_47

; #define LAS __attribute__((address_space(3)))
; DI float h2f(bf16_t v) { return (float)__builtin_bit_cast(_Float16, v); }
; DI float bf2f(bf16_t v) { return __uint_as_float(((unsigned)v) << 16); }
; DI void lds_barrier() { asm volatile("s_waitcnt lgkmcnt(0)\n\ts_barrier" ::: "memory"); }
;     ...
;   for (int k0 = kbeg; k0 < kend; k0 += 64) {
;     lds_barrier();
; #pragma unroll
;     for (int rr = 0; rr < 2; ++rr) { const int k = k0 + kr + rr * 32; const float gk = g ? g[k] : 1.0f, bk = b ? b[k] : 0.0f;
; #pragma unroll
;       for (int j = 0; j < 4; ++j) { const bf16_t v = perm ? f2h(w[rr][j] * gk) : f2bf(w[rr][j] * gk); tile[(nc + j) * 72 + kr + rr * 32] = v; s1[j] += perm ? h2f(v) : bf2f(v); s2[j] += bk * w[rr][j]; } }
;     if (k0 + 64 < kend) {
; #pragma unroll
;       for (int rr = 0; rr < 2; ++rr) w[rr] = colok ? *(const f32x4*)(src + (size_t)(k0 + 64 + kr + rr * 32) * ldn + n0 + nc) : (f32x4){0.f, 0.f, 0.f, 0.f};
;     }
;     lds_barrier();
;     { const int n = tid >> 3, kc = (tid & 7) * 8; const int cc = n & 31, slot = (n & 32) + (perm ? 16 * ((cc >> 2) & 1) + 4 * (cc >> 3) + (cc & 3) : cc);
;       *(u32x4*)(dst + (size_t)(dstrow0 + slot) * K + k0 + kc) = *(const LAS u32x4*)(tile + n * 72 + kc); }
;   }
; DI void convert_phase(int wv, const P& p_, int L, LAS unsigned char* lds) {
;     ...
;     if (j < 272) {
;       const int f = j / 136, jj = j % 136;
;       const float* lg = p.ln_gain + (size_t)(L * 3 + (f == 0 ? -1 : 1)) * DM; const float* lbias = p.ln_bias + (size_t)(L * 3 + (f == 0 ? -1 : 1)) * DM;
;       const bool fold = !(L == 0 && f == 0);
;       float* cbase = (float*)(ws + (f == 0 ? C_GU1 : C_GU2));
;       if (jj < 88) {
;         const int up = jj / 44, s = jj % 44, n0 = s * 64;
;         const float* src = (f == 0 ? (up ? p.f1u : p.f1g) : (up ? p.f2u : p.f2g)) + (size_t)L * DM * DFF;
;         conv_strip(wv, lds, src, DFF, DM, n0, DFF, (bf16_t*)(ws + (f == 0 ? W_GU1 : W_GU2)), (n0 >> 7) * 256 + (n0 & 127) + up * 128, fold ? lg : nullptr, fold ? lbias : nullptr, cbase, cbase + 5632);
;       } else {
;         const int s = (jj - 88) / 3, kc = (jj - 88) % 3;
;         const float* src = (f == 0 ? p.f1d : p.f2d) + (size_t)L * DFF * DM;
;         conv_strip(wv, lds, src, DM, DFF, s * 64, DM, (bf16_t*)(ws + (f == 0 ? W_D1 : W_D2)), s * 64, nullptr, nullptr, nullptr, nullptr, true, kc * 960, kc == 2 ? DFF : kc * 960 + 960);
.LBB0_103:
	s_andn2_b64 vcc, exec, s[0:1]
	s_cbranch_vccnz .LBB0_38
	s_mul_hi_i32 s0, s87, 0x78787879
	s_lshr_b32 s1, s0, 31
	s_ashr_i32 s0, s0, 6
	s_add_i32 s0, s0, s1
	s_mulk_i32 s0, 0x88
	s_sub_i32 s27, s87, s0
	s_add_i32 s0, s87, 0x87
	s_cmpk_lt_u32 s0, 0x10f
	s_cselect_b64 s[78:79], -1, 0
	s_cmpk_gt_i32 s27, 0x57
	s_mov_b64 s[0:1], -1
	s_cbranch_scc0 .LBB0_111
	s_add_i32 s29, s27, 0xffa8
	s_and_b32 s0, s29, 0xff
	s_mul_i32 s1, s0, 0xab
	s_bfe_u32 s1, s1, 0x70009
	s_mul_i32 s30, s1, 3
	s_sub_i32 s29, s29, s30
	s_and_b32 s30, s29, 0xff
	s_mul_i32 s29, s30, 0x3c0
	s_add_i32 s31, s29, 0x3c0
	s_cmp_lg_u32 s30, 2
	s_cselect_b32 s30, s31, 0xb00
	s_waitcnt vmcnt(1)
	v_mbcnt_lo_u32_b32 v0, -1, 0
	v_mbcnt_hi_u32_b32 v0, -1, v0
	s_cmp_ge_u32 s29, s30
	v_add_u32_e32 v8, s69, v0
	s_cbranch_scc1 .LBB0_110
	v_readlane_b32 s60, v252, 16
	v_readlane_b32 s61, v252, 17
	v_readlane_b32 s62, v252, 18
	v_readlane_b32 s63, v252, 19
	v_readlane_b32 s64, v252, 20
	v_readlane_b32 s65, v252, 21
	v_readlane_b32 s66, v252, 22
	v_readlane_b32 s67, v252, 23
	v_readlane_b32 s68, v252, 24
	v_readlane_b32 s69, v252, 25
	v_readlane_b32 s70, v252, 26
	v_readlane_b32 s71, v252, 27
	s_and_b32 s1, 0xffff, s1
	v_readlane_b32 s72, v252, 28
	v_readlane_b32 s73, v252, 29
	v_readlane_b32 s74, v252, 30
	v_readlane_b32 s75, v252, 31
	s_mov_b64 s[60:61], s[64:65]
	v_readlane_b32 s4, v252, 32
	s_and_b64 s[34:35], s[78:79], exec
	s_mov_b64 s[62:63], s[66:67]
	s_mov_b64 s[64:65], s[68:69]
	s_mov_b64 s[66:67], s[70:71]
	s_mov_b64 s[68:69], s[72:73]
	v_readlane_b32 s6, v252, 34
	v_readlane_b32 s7, v252, 35
	s_cselect_b32 s36, s68, s6
	s_cselect_b32 s31, s69, s7
	s_add_u32 s34, s36, s93
	s_addc_u32 s35, s31, 0
	s_lshl_b32 s37, s1, 6
	v_ashrrev_i32_e32 v12, 4, v8
	v_lshlrev_b32_e32 v0, 2, v8
	s_lshl_b32 s38, s1, 8
	v_and_b32_e32 v9, 60, v0
	s_add_u32 s34, s34, s38
	v_add_u32_e32 v2, s29, v12
	s_addc_u32 s35, s35, 0
	v_lshlrev_b32_e32 v0, 2, v9
	v_mov_b32_e32 v1, v32
	v_ashrrev_i32_e32 v3, 31, v2
	v_lshl_add_u64 v[0:1], s[34:35], 0, v[0:1]
	v_lshlrev_b64 v[2:3], 12, v[2:3]
	v_lshl_add_u64 v[0:1], v[0:1], 0, v[2:3]
	s_mov_b32 s34, 0x20000
	v_add_co_u32_e32 v2, vcc, s34, v0
	v_ashrrev_i32_e32 v10, 3, v8
	s_nop 0
	v_addc_co_u32_e32 v3, vcc, 0, v1, vcc
	global_load_dwordx4 v[4:7], v[2:3], off
	s_nop 0
	global_load_dwordx4 v[0:3], v[0:1], off
	v_lshrrev_b32_e32 v13, 1, v10
	v_lshlrev_b32_e32 v16, 4, v8
	v_lshlrev_b32_e32 v11, 2, v10
	v_and_b32_e32 v13, 12, v13
	v_mul_lo_u32 v14, v10, s90
	v_and_b32_e32 v17, 0x70, v16
	v_and_b32_e32 v11, 16, v11
	v_add3_u32 v14, 0, v14, v17
	v_mul_u32_u24_e32 v17, 0x90, v9
	v_and_or_b32 v9, v10, 35, v13
	s_and_b64 s[34:35], s[78:79], exec
	s_mov_b32 s6, 0x1b80000
	v_or3_b32 v9, v9, v11, s37
	s_cselect_b32 s34, 0xb00000, s6
	v_mul_u32_u24_e32 v10, 0xb00, v9
	v_and_b32_e32 v8, 7, v8
	v_lshl_or_b32 v8, v8, 4, s34
	v_mov_b32_e32 v9, v32
	v_lshlrev_b32_e32 v10, 1, v10
	v_mov_b32_e32 v11, v32
	s_mul_i32 s37, s0, 0x3c0
	v_lshl_add_u64 v[8:9], v[8:9], 0, v[10:11]
	s_lshl_b32 s34, s29, 1
	s_mulk_i32 s1, 0xb40
	v_add_u32_e32 v10, s37, v12
	v_lshl_add_u32 v15, v12, 1, 0
	s_add_u32 s34, s94, s34
	v_subrev_u32_e32 v12, s1, v10
	s_addc_u32 s35, s95, 0
	v_readlane_b32 s6, v255, 6
	v_add_u32_e32 v10, 0x60, v12
	v_lshl_add_u64 v[8:9], s[34:35], 0, v[8:9]
	v_readlane_b32 s7, v255, 7
	s_add_u32 s34, s36, s6
	v_ashrrev_i32_e32 v11, 31, v10
	s_mul_hi_u32 s0, s0, 0x55555556
	v_ashrrev_i32_e32 v13, 31, v12
	s_addc_u32 s35, s31, s7
	v_lshlrev_b64 v[10:11], 12, v[10:11]
	s_lshl_b32 s84, s0, 8
	v_readlane_b32 s0, v255, 14
	v_lshlrev_b64 v[12:13], 12, v[12:13]
	v_readlane_b32 s5, v252, 33
	v_lshl_add_u64 v[10:11], v[10:11], 0, s[84:85]
	v_and_b32_e32 v16, 0xf0, v16
	v_readlane_b32 s1, v255, 15
	s_add_u32 s0, s36, s0
	v_lshl_add_u64 v[12:13], v[12:13], 0, s[84:85]
	s_mov_b64 s[70:71], s[74:75]
	v_readlane_b32 s72, v255, 24
	v_readlane_b32 s4, v252, 56
	v_or_b32_e32 v10, v10, v16
	s_addc_u32 s1, s31, s1
	v_or_b32_e32 v12, v12, v16
	s_mov_b32 s60, 0xf149f2ca
	s_movk_i32 s65, 0xa00
	v_readlane_b32 s64, v255, 30
	v_readlane_b32 s75, v255, 28
	v_readlane_b32 s74, v255, 27
	v_readlane_b32 s67, v255, 26
	v_readlane_b32 s73, v255, 25
	v_readlane_b32 s66, v255, 23
	v_readlane_b32 s5, v252, 57
	s_mov_b32 s69, s48
	s_mov_b32 s68, s44
	v_lshl_add_u64 v[10:11], s[34:35], 0, v[10:11]
	v_lshl_add_u64 v[12:13], s[0:1], 0, v[12:13]
	v_add_u32_e32 v15, v15, v17
	v_readlane_b32 s8, v252, 36
	v_readlane_b32 s9, v252, 37
	v_readlane_b32 s10, v252, 38
	v_readlane_b32 s11, v252, 39
	v_readlane_b32 s12, v252, 40
	v_readlane_b32 s13, v252, 41
	v_readlane_b32 s14, v252, 42
	v_readlane_b32 s15, v252, 43
	v_readlane_b32 s16, v252, 44
	v_readlane_b32 s17, v252, 45
	v_readlane_b32 s18, v252, 46
	v_readlane_b32 s19, v252, 47
	s_mov_b64 s[100:101], 0x40000
	global_load_dwordx4 v[244:247], v[12:13], off
	s_nop 0
	global_load_dwordx4 v[248:251], v[10:11], off
	s_waitcnt vmcnt(2)
	s_branch .LBB0_108
.LBB0_108:
	v_cvt_f16_f32_e32 v16, v0
	v_cvt_f16_f32_e32 v17, v1
	v_cvt_f16_f32_e32 v18, v2
	v_cvt_f16_f32_e32 v19, v3
	s_waitcnt lgkmcnt(0)
	s_barrier
	ds_write_b16 v15, v16
	ds_write_b16 v15, v17 offset:144
	ds_write_b16 v15, v18 offset:288
	ds_write_b16 v15, v19 offset:432
	v_cvt_f16_f32_e32 v16, v4
	s_add_i32 s29, s29, 64
	v_cvt_f16_f32_e32 v17, v5
	s_cmp_ge_u32 s29, s30
	v_cvt_f16_f32_e32 v18, v6
	s_cselect_b64 s[0:1], -1, 0
	v_cvt_f16_f32_e32 v19, v7
	s_and_b64 vcc, exec, s[0:1]
	ds_write_b16 v15, v16 offset:64
	ds_write_b16 v15, v17 offset:208
	ds_write_b16 v15, v18 offset:352
	ds_write_b16 v15, v19 offset:496
	s_cbranch_vccnz .Lc108a_107
	s_add_i32 s98, s29, 64
	s_cmp_lt_u32 s98, s30
	s_cbranch_scc0 .Lc108a_107
	v_lshl_add_u64 v[220:221], v[12:13], 0, s[100:101]
	v_lshl_add_u64 v[224:225], v[10:11], 0, s[100:101]
	global_load_dwordx4 v[220:223], v[220:221], off
	s_nop 0
	global_load_dwordx4 v[224:227], v[224:225], off
.Lc108a_107:
	s_waitcnt lgkmcnt(0)
	s_barrier
	ds_read_b128 v[16:19], v14
	s_mov_b64 s[6:7], 0x40000
	v_lshl_add_u64 v[10:11], v[10:11], 0, s[6:7]
	s_andn2_b64 vcc, exec, s[0:1]
	v_lshl_add_u64 v[12:13], v[12:13], 0, s[6:7]
	s_waitcnt lgkmcnt(0)
	global_store_dwordx4 v[8:9], v[16:19], off
	v_lshl_add_u64 v[8:9], v[8:9], 0, s[2:3]
	s_cbranch_vccz .LBB0_110
	s_add_i32 s98, s29, 64
	s_cmp_lt_u32 s98, s30
	s_cbranch_scc1 .Lc108a_w3
	s_waitcnt vmcnt(1)
	s_branch .Lc108a_cp

; #define LAS __attribute__((address_space(3)))
; DI float h2f(bf16_t v) { return (float)__builtin_bit_cast(_Float16, v); }
; DI float bf2f(bf16_t v) { return __uint_as_float(((unsigned)v) << 16); }
; DI void lds_barrier() { asm volatile("s_waitcnt lgkmcnt(0)\n\ts_barrier" ::: "memory"); }
;     ...
;   for (int k0 = kbeg; k0 < kend; k0 += 64) {
;     lds_barrier();
; #pragma unroll
;     for (int rr = 0; rr < 2; ++rr) { const int k = k0 + kr + rr * 32; const float gk = g ? g[k] : 1.0f, bk = b ? b[k] : 0.0f;
; #pragma unroll
;       for (int j = 0; j < 4; ++j) { const bf16_t v = perm ? f2h(w[rr][j] * gk) : f2bf(w[rr][j] * gk); tile[(nc + j) * 72 + kr + rr * 32] = v; s1[j] += perm ? h2f(v) : bf2f(v); s2[j] += bk * w[rr][j]; } }
;     if (k0 + 64 < kend) {
; #pragma unroll
;       for (int rr = 0; rr < 2; ++rr) w[rr] = colok ? *(const f32x4*)(src + (size_t)(k0 + 64 + kr + rr * 32) * ldn + n0 + nc) : (f32x4){0.f, 0.f, 0.f, 0.f};
;     }
;     lds_barrier();
;     { const int n = tid >> 3, kc = (tid & 7) * 8; const int cc = n & 31, slot = (n & 32) + (perm ? 16 * ((cc >> 2) & 1) + 4 * (cc >> 3) + (cc & 3) : cc);
;       *(u32x4*)(dst + (size_t)(dstrow0 + slot) * K + k0 + kc) = *(const LAS u32x4*)(tile + n * 72 + kc); }
;   }
.Lc108a_cp:
	v_mov_b32_e32 v0, v244
	v_mov_b32_e32 v1, v245
	v_mov_b32_e32 v2, v246
	v_mov_b32_e32 v3, v247
	v_mov_b32_e32 v4, v248
	v_mov_b32_e32 v5, v249
	v_mov_b32_e32 v6, v250
	v_mov_b32_e32 v7, v251
.Lc108b_top:
	v_cvt_f16_f32_e32 v16, v0
	v_cvt_f16_f32_e32 v17, v1
	v_cvt_f16_f32_e32 v18, v2
	v_cvt_f16_f32_e32 v19, v3
	s_waitcnt lgkmcnt(0)
	s_barrier
	ds_write_b16 v15, v16
	ds_write_b16 v15, v17 offset:144
	ds_write_b16 v15, v18 offset:288
	ds_write_b16 v15, v19 offset:432
	v_cvt_f16_f32_e32 v16, v4
	s_add_i32 s29, s29, 64
	v_cvt_f16_f32_e32 v17, v5
	s_cmp_ge_u32 s29, s30
	v_cvt_f16_f32_e32 v18, v6
	s_cselect_b64 s[0:1], -1, 0
	v_cvt_f16_f32_e32 v19, v7
	s_and_b64 vcc, exec, s[0:1]
	ds_write_b16 v15, v16 offset:64
	ds_write_b16 v15, v17 offset:208
	ds_write_b16 v15, v18 offset:352
	ds_write_b16 v15, v19 offset:496
	s_cbranch_vccnz .Lc108b_107
	s_add_i32 s98, s29, 64
	s_cmp_lt_u32 s98, s30
	s_cbranch_scc0 .Lc108b_107
	v_lshl_add_u64 v[244:245], v[12:13], 0, s[100:101]
	v_lshl_add_u64 v[248:249], v[10:11], 0, s[100:101]
	global_load_dwordx4 v[244:247], v[244:245], off
	s_nop 0
	global_load_dwordx4 v[248:251], v[248:249], off

;     ...
;     if (k0 + 64 < kend) {
; #pragma unroll
;       for (int rr = 0; rr < 2; ++rr) w[rr] = colok ? *(const f32x4*)(src + (size_t)(k0 + 64 + kr + rr * 32) * ldn + n0 + nc) : (f32x4){0.f, 0.f, 0.f, 0.f};
;     }
.Lc108b_cp:
	v_mov_b32_e32 v0, v220
	v_mov_b32_e32 v1, v221
	v_mov_b32_e32 v2, v222
	v_mov_b32_e32 v3, v223
	v_mov_b32_e32 v4, v224
	v_mov_b32_e32 v5, v225
	v_mov_b32_e32 v6, v226
	v_mov_b32_e32 v7, v227
	s_branch .LBB0_108

; DI float h2f(bf16_t v) { return (float)__builtin_bit_cast(_Float16, v); }
; DI float bf2f(bf16_t v) { return __uint_as_float(((unsigned)v) << 16); }
; DI void lds_barrier() { asm volatile("s_waitcnt lgkmcnt(0)\n\ts_barrier" ::: "memory"); }
;     ...
;   for (int rr = 0; rr < 2; ++rr) w[rr] = colok ? *(const f32x4*)(src + (size_t)(kbeg + kr + rr * 32) * ldn + n0 + nc) : (f32x4){0.f, 0.f, 0.f, 0.f};
;   for (int k0 = kbeg; k0 < kend; k0 += 64) {
;     lds_barrier();
; #pragma unroll
;     for (int rr = 0; rr < 2; ++rr) { const int k = k0 + kr + rr * 32; const float gk = g ? g[k] : 1.0f, bk = b ? b[k] : 0.0f;
; #pragma unroll
;       for (int j = 0; j < 4; ++j) { const bf16_t v = perm ? f2h(w[rr][j] * gk) : f2bf(w[rr][j] * gk); tile[(nc + j) * 72 + kr + rr * 32] = v; s1[j] += perm ? h2f(v) : bf2f(v); s2[j] += bk * w[rr][j]; } }
;     if (k0 + 64 < kend) {
; #pragma unroll
;       for (int rr = 0; rr < 2; ++rr) w[rr] = colok ? *(const f32x4*)(src + (size_t)(k0 + 64 + kr + rr * 32) * ldn + n0 + nc) : (f32x4){0.f, 0.f, 0.f, 0.f};
;     }
.Lconv113_nb0:
	s_waitcnt vmcnt(0)
	s_add_u32 s98, s34, s6
	s_addc_u32 s99, s35, s7
	v_lshl_add_u64 v[244:245], v[34:35], 0, s[34:35]
	v_lshl_add_u64 v[248:249], v[30:31], 0, s[34:35]
	global_load_dwordx4 v[244:247], v[244:245], off
	s_nop 0
	global_load_dwordx4 v[248:251], v[248:249], off

; DI float h2f(bf16_t v) { return (float)__builtin_bit_cast(_Float16, v); }
; DI float bf2f(bf16_t v) { return __uint_as_float(((unsigned)v) << 16); }
;     ...
;     for (int rr = 0; rr < 2; ++rr) { const int k = k0 + kr + rr * 32; const float gk = g ? g[k] : 1.0f, bk = b ? b[k] : 0.0f;
; #pragma unroll
;       for (int j = 0; j < 4; ++j) { const bf16_t v = perm ? f2h(w[rr][j] * gk) : f2bf(w[rr][j] * gk); tile[(nc + j) * 72 + kr + rr * 32] = v; s1[j] += perm ? h2f(v) : bf2f(v); s2[j] += bk * w[rr][j]; } }
.Lc113a_117:
	v_fma_mixlo_f16 v41, v0, v16, 0
	v_fma_mixlo_f16 v43, v1, v16, 0
	v_fma_mixlo_f16 v44, v2, v16, 0
	v_fma_mixlo_f16 v45, v3, v16, 0
	s_andn2_b64 vcc, exec, s[36:37]
	v_mov_b32_e32 v16, 1.0
	ds_write_b16 v25, v41
	ds_write_b16 v25, v43 offset:144
	ds_write_b16 v25, v44 offset:288
	ds_write_b16 v25, v45 offset:432
	s_cbranch_vccnz .Lc113a_119
	v_mov_b32_e32 v16, v218

; DI float h2f(bf16_t v) { return (float)__builtin_bit_cast(_Float16, v); }
; DI float bf2f(bf16_t v) { return __uint_as_float(((unsigned)v) << 16); }
;     ...
;     for (int rr = 0; rr < 2; ++rr) { const int k = k0 + kr + rr * 32; const float gk = g ? g[k] : 1.0f, bk = b ? b[k] : 0.0f;
; #pragma unroll
;       for (int j = 0; j < 4; ++j) { const bf16_t v = perm ? f2h(w[rr][j] * gk) : f2bf(w[rr][j] * gk); tile[(nc + j) * 72 + kr + rr * 32] = v; s1[j] += perm ? h2f(v) : bf2f(v); s2[j] += bk * w[rr][j]; } }
;     if (k0 + 64 < kend) {
; #pragma unroll
;       for (int rr = 0; rr < 2; ++rr) w[rr] = colok ? *(const f32x4*)(src + (size_t)(k0 + 64 + kr + rr * 32) * ldn + n0 + nc) : (f32x4){0.f, 0.f, 0.f, 0.f};
;     }
.Lc113a_121:
	s_cmpk_gt_u32 s31, 0x3bf
	v_fma_mixlo_f16 v46, v4, v16, 0
	v_fma_mixlo_f16 v47, v5, v16, 0
	v_fma_mixlo_f16 v48, v6, v16, 0
	v_fma_mixlo_f16 v49, v7, v16, 0
	s_cselect_b64 s[0:1], -1, 0
	s_cmpk_lt_u32 s31, 0x3c0
	ds_write_b16 v25, v46 offset:64
	ds_write_b16 v25, v47 offset:208
	ds_write_b16 v25, v48 offset:352
	ds_write_b16 v25, v49 offset:496
	s_cbranch_scc0 .Lc113a_123
	s_and_b64 vcc, exec, s[36:37]
	s_cbranch_vccz .Lc113a_ng
	global_load_dword v216, v[38:39], off offset:128
	global_load_dword v218, v[38:39], off offset:256

; #define LAS __attribute__((address_space(3)))
; DI float h2f(bf16_t v) { return (float)__builtin_bit_cast(_Float16, v); }
; DI float bf2f(bf16_t v) { return __uint_as_float(((unsigned)v) << 16); }
; DI void lds_barrier() { asm volatile("s_waitcnt lgkmcnt(0)\n\ts_barrier" ::: "memory"); }
;     ...
;   for (int k0 = kbeg; k0 < kend; k0 += 64) {
;     lds_barrier();
; #pragma unroll
;     for (int rr = 0; rr < 2; ++rr) { const int k = k0 + kr + rr * 32; const float gk = g ? g[k] : 1.0f, bk = b ? b[k] : 0.0f;
; #pragma unroll
;       for (int j = 0; j < 4; ++j) { const bf16_t v = perm ? f2h(w[rr][j] * gk) : f2bf(w[rr][j] * gk); tile[(nc + j) * 72 + kr + rr * 32] = v; s1[j] += perm ? h2f(v) : bf2f(v); s2[j] += bk * w[rr][j]; } }
;     if (k0 + 64 < kend) {
; #pragma unroll
;       for (int rr = 0; rr < 2; ++rr) w[rr] = colok ? *(const f32x4*)(src + (size_t)(k0 + 64 + kr + rr * 32) * ldn + n0 + nc) : (f32x4){0.f, 0.f, 0.f, 0.f};
;     }
;     lds_barrier();
;     { const int n = tid >> 3, kc = (tid & 7) * 8; const int cc = n & 31, slot = (n & 32) + (perm ? 16 * ((cc >> 2) & 1) + 4 * (cc >> 3) + (cc & 3) : cc);
;       *(u32x4*)(dst + (size_t)(dstrow0 + slot) * K + k0 + kc) = *(const LAS u32x4*)(tile + n * 72 + kc); }
;   }
.Lc113a_nb:
	s_cmpk_lt_u32 s31, 0x380
	s_cbranch_scc0 .Lc113a_123
	v_lshl_add_u64 v[220:221], v[34:35], 0, s[98:99]
	v_lshl_add_u64 v[224:225], v[30:31], 0, s[98:99]
	global_load_dwordx4 v[220:223], v[220:221], off
	s_nop 0
	global_load_dwordx4 v[224:227], v[224:225], off
.Lc113a_123:
	v_cvt_f32_f16_e32 v44, v44
	v_cvt_f32_f16_e32 v45, v45
	v_cvt_f32_f16_e32 v41, v41
	v_cvt_f32_f16_e32 v43, v43
	v_add_f32_e32 v10, v10, v44
	v_add_f32_e32 v11, v11, v45
	v_cvt_f32_f16_e32 v44, v48
	v_cvt_f32_f16_e32 v45, v49
	s_waitcnt lgkmcnt(0)
	s_barrier
	v_add_f32_e32 v8, v8, v41
	v_add_f32_e32 v9, v9, v43
	v_cvt_f32_f16_e32 v41, v46
	v_cvt_f32_f16_e32 v43, v47
	v_add_f32_e32 v10, v10, v44
	v_add_f32_e32 v11, v11, v45
	ds_read_b128 v[44:47], v27
	v_pk_fma_f32 v[0:1], v[0:1], v[40:41], v[12:13] op_sel_hi:[1,0,1]
	v_pk_fma_f32 v[2:3], v[2:3], v[40:41], v[14:15] op_sel_hi:[1,0,1]
	s_mov_b64 s[8:9], 0x100
	v_add_f32_e32 v8, v8, v41
	v_add_f32_e32 v9, v9, v43
	v_pk_fma_f32 v[12:13], v[4:5], v[42:43], v[0:1] op_sel_hi:[1,0,1]
	v_pk_fma_f32 v[14:15], v[6:7], v[42:43], v[2:3] op_sel_hi:[1,0,1]
	s_add_i32 s31, s31, 64
	s_waitcnt lgkmcnt(0)
	global_store_dwordx4 v[28:29], v[44:47], off
	v_lshl_add_u64 v[28:29], v[28:29], 0, s[2:3]
	v_lshl_add_u64 v[30:31], v[30:31], 0, s[6:7]
	v_lshl_add_u64 v[34:35], v[34:35], 0, s[6:7]
	v_lshl_add_u64 v[36:37], v[36:37], 0, s[8:9]
	v_lshl_add_u64 v[38:39], v[38:39], 0, s[8:9]
	s_and_b64 vcc, exec, s[0:1]
	s_cbranch_vccnz .LBB0_125
	s_cmpk_lt_u32 s31, 0x3c0
	s_cbranch_scc1 .Lc113a_w3
	s_waitcnt vmcnt(1)
	s_branch .Lc113a_cp

;     ...
;     if (k0 + 64 < kend) {
; #pragma unroll
;       for (int rr = 0; rr < 2; ++rr) w[rr] = colok ? *(const f32x4*)(src + (size_t)(k0 + 64 + kr + rr * 32) * ldn + n0 + nc) : (f32x4){0.f, 0.f, 0.f, 0.f};
;     }
.Lc113b_nb:
	s_cmpk_lt_u32 s31, 0x380
	s_cbranch_scc0 .Lc113b_123
	v_lshl_add_u64 v[244:245], v[34:35], 0, s[98:99]
	v_lshl_add_u64 v[248:249], v[30:31], 0, s[98:99]
	global_load_dwordx4 v[244:247], v[244:245], off
	s_nop 0
	global_load_dwordx4 v[248:251], v[248:249], off
